# kernel entry: all kernarg scalar loads issued together (one round trip instead of three)
# baseline (speedup 1.0000x reference)
; #define LAS __attribute__((address_space(3)))
; __global__ void __launch_bounds__(NTHR, 2) hybrid_fwd(Args a) {
;     extern __shared__ __attribute__((aligned(16))) unsigned char lds_raw[];
;     LAS unsigned char* lds = (LAS unsigned char*)lds_raw;
;     const int tid = threadIdx.x, lane = tid & 63, wave = __builtin_amdgcn_readfirstlane(tid >> 6);
;     const int G = gridDim.x, bx = blockIdx.x;
;     const int vcu = (G % 8 == 0) ? (bx % 8) * (G / 8) + bx / 8 : bx;
;     const int gw = vcu * NWAVES + wave, NGW = G * NWAVES;
;     unsigned char* ws = a.ws;
;     float* MOD = (float*)(ws + WS_MOD); float* SWp = (float*)(ws + WS_SW); float* SSQ = (float*)(ws + WS_SSQ);
;     bf16_t* WAB = (bf16_t*)(ws + WS_WAB); bf16_t* WOAB = (bf16_t*)(ws + WS_WOAB); bf16_t* WC = (bf16_t*)(ws + WS_WC); bf16_t* WOC = (bf16_t*)(ws + WS_WOC);
;     bf16_t* H0 = (bf16_t*)(ws + WS_H0); bf16_t* Y = (bf16_t*)(ws + WS_Y);
;     bf16_t* Ub = (bf16_t*)(ws + WS_U); bf16_t* Gb = (bf16_t*)(ws + WS_G); bf16_t* UZb = (bf16_t*)(ws + WS_UZ); bf16_t* Vb = (bf16_t*)(ws + WS_V);
;     bf16_t* X1 = (bf16_t*)(ws + WS_X1); bf16_t* H1 = (bf16_t*)(ws + WS_H1);
;     bf16_t* Qb = (bf16_t*)(ws + WS_Q); bf16_t* Kb = (bf16_t*)(ws + WS_K); bf16_t* Zb = (bf16_t*)(ws + WS_Z); bf16_t* VTb = (bf16_t*)(ws + WS_VT); bf16_t* OZb = (bf16_t*)(ws + WS_OZ);
;     const int lo = a.ph_lo, hi = a.ph_hi;
;     ...
;     volatile LAS unsigned* bst = (volatile LAS unsigned*)(lds + LDS_BYTES - 64);
;     if (tid < 4) bst[tid] = 0u;
;     __syncthreads();
;     XcdBarrier xbar; xbar.bar = (unsigned*)(ws + WS_CTL); xbar.x = 0; xbar.st = bst;
;     if (hi - lo > 1) xbar = xcd_barrier_post((unsigned*)(ws + WS_CTL), bst);
_Z10hybrid_fwd4Args:
	s_load_dwordx2 s[54:55], s[0:1], 0x88
	s_load_dword s3, s[0:1], 0x90
	s_load_dwordx2 s[52:53], s[0:1], 0x80
	s_load_dwordx16 s[16:31], s[0:1], 0x0
	s_load_dwordx16 s[36:51], s[0:1], 0x40
	s_add_u32 s4, s0, 0x90
	s_addc_u32 s5, s1, 0
	v_readfirstlane_b32 s8, v0
	v_writelane_b32 v253, s4, 0
	s_mov_b32 s78, s2
	s_mov_b32 s84, s2
	v_writelane_b32 v253, s5, 1
	s_waitcnt lgkmcnt(0)
	s_and_b32 s4, s3, 7
	s_cmp_lg_u32 s4, 0
	s_cbranch_scc0 .LBB0_31
	v_cmp_gt_u32_e32 vcc, 4, v0
	s_and_saveexec_b64 s[4:5], vcc

; #define LAS __attribute__((address_space(3)))
; __global__ void __launch_bounds__(NTHR, 2) hybrid_fwd(Args a) {
;     ...
;     if (IN(0)) {
;         for (int task = bx; task < 192; task += G) {
;             LAS float* sc_l = (LAS float*)lds; LAS float* red = sc_l + 2048;
;             for (int i = tid; i < BATCH * D; i += NTHR) { const float v = a.c[i]; sc_l[i] = v / (1.0f + __expf(-v)); }
;             __syncthreads();
;             const int l = task / 96, n0 = (task % 96) * 32, kc = wave * 2 + (lane >> 5), n = n0 + (lane & 31);
;             const float* W = a.ada_w + (size_t)l * D * 3072 + (size_t)(kc * 64) * 3072 + n;
;             float a0 = 0.f, a1 = 0.f;
; #pragma unroll
;             for (int k = 0; k < 64; ++k) { const float wv = W[(size_t)k * 3072]; a0 += sc_l[kc * 64 + k] * wv; a1 += sc_l[D + kc * 64 + k] * wv; }
.LBB0_8:
	s_lshr_b32 s79, s8, 6
	s_lshl_b32 s0, s84, 3
	s_add_i32 s34, s0, s79
	s_lshl_b32 s66, s3, 3
	s_add_u32 s60, s52, 0x100000
	s_addc_u32 s61, s53, 0
	s_add_u32 s62, s52, 0x200000
	s_addc_u32 s63, s53, 0
	s_cmp_lt_i32 s54, 1
	s_cselect_b64 s[0:1], -1, 0
	s_cmp_gt_i32 s55, 0
	s_cselect_b64 s[4:5], -1, 0
	s_and_b64 s[0:1], s[0:1], s[4:5]
	s_andn2_b64 vcc, exec, s[0:1]
	v_and_b32_e32 v154, 63, v0
	s_cbranch_vccnz .LBB0_96
	s_cmpk_gt_i32 s2, 0xbf
	s_cbranch_scc1 .LBB0_16
	v_lshrrev_b32_e32 v1, 5, v154
	v_lshl_or_b32 v4, s79, 1, v1
	s_waitcnt lgkmcnt(0)
	v_mov_b32_e32 v2, s22
	v_mov_b32_e32 v3, s23
	v_lshlrev_b32_e32 v5, 6, v4
	s_movk_i32 s8, 0x3000
	v_and_b32_e32 v1, 31, v0
	v_mad_u64_u32 v[14:15], s[0:1], v5, s8, v[2:3]
	v_and_b32_e32 v3, 32, v0
	v_lshl_add_u32 v20, v4, 8, 0
	v_lshlrev_b32_e32 v2, 2, v1
	v_lshlrev_b32_e32 v3, 2, v3
	v_add_u32_e32 v4, v20, v2
	v_add3_u32 v22, 0, v3, v2
	v_lshlrev_b32_e32 v2, 2, v0
	v_mov_b32_e32 v3, 0
	v_lshrrev_b32_e32 v21, 5, v0
	v_or_b32_e32 v23, 0xfffffe00, v0
	v_lshl_add_u64 v[16:17], s[18:19], 0, v[2:3]
	v_add_u32_e32 v24, 0, v2
	v_mov_b32_e32 v25, 0xc00000
	s_mov_b32 s9, 0x3c000
	s_mov_b32 s10, 0x3f000
	s_mov_b32 s11, 0x42000
	s_mov_b32 s12, 0x45000
	s_mov_b32 s13, 0x48000
	s_mov_b32 s14, 0x4b000
	s_mov_b32 s15, 0x4e000
	s_mov_b32 s18, 0x51000
	s_mov_b32 s19, 0x54000
	s_mov_b32 s22, 0x57000
	s_mov_b32 s23, 0x5a000
	s_mov_b32 s35, 0x5d000
	s_mov_b32 s56, 0x60000
	s_mov_b32 s57, 0x63000
	s_mov_b32 s64, 0x66000
	s_mov_b32 s65, 0x69000
	s_mov_b32 s67, 0x6c000
	s_mov_b32 s68, 0x6f000
	s_mov_b32 s69, 0x72000
	s_mov_b32 s70, 0x75000
	s_mov_b32 s71, 0x78000
	s_mov_b32 s72, 0x7b000
	s_mov_b32 s73, 0x7e000
	s_mov_b32 s74, 0x81000
	s_mov_b32 s75, 0x84000
	s_mov_b32 s76, 0x87000
	s_mov_b32 s77, 0x8a000
	s_mov_b32 s80, 0x8d000
	s_mov_b32 s81, 0x90000
	s_mov_b32 s82, 0x93000
	s_mov_b32 s83, 0x96000
	s_mov_b32 s85, 0x99000
	s_mov_b32 s86, 0x9c000
	s_mov_b32 s87, 0x9f000
	s_mov_b32 s88, 0xa2000
	s_mov_b32 s89, 0xa5000
	s_mov_b32 s90, 0xa8000
	s_mov_b32 s91, 0xab000
	v_add_u32_e32 v26, 0x2000, v4
	s_mov_b32 s92, 0xae000
	s_mov_b32 s93, 0xb1000
	s_mov_b32 s94, 0xb4000
	s_mov_b32 s95, 0xb7000
	s_mov_b32 s96, 0xba000
	s_movk_i32 s97, 0xc00
	s_mov_b32 s98, s78
	v_cmp_gt_u32_e64 s[0:1], 64, v0
	s_mov_b64 s[4:5], 0x800
	s_branch .LBB0_12

; #define LAS __attribute__((address_space(3)))
; __global__ void __launch_bounds__(NTHR, 2) hybrid_fwd(Args a) {
;     ...
;     const int vcu = (G % 8 == 0) ? (bx % 8) * (G / 8) + bx / 8 : bx;
;     const int gw = vcu * NWAVES + wave, NGW = G * NWAVES;
;     unsigned char* ws = a.ws;
;     float* MOD = (float*)(ws + WS_MOD); float* SWp = (float*)(ws + WS_SW); float* SSQ = (float*)(ws + WS_SSQ);
;     bf16_t* WAB = (bf16_t*)(ws + WS_WAB); bf16_t* WOAB = (bf16_t*)(ws + WS_WOAB); bf16_t* WC = (bf16_t*)(ws + WS_WC); bf16_t* WOC = (bf16_t*)(ws + WS_WOC);
;     bf16_t* H0 = (bf16_t*)(ws + WS_H0); bf16_t* Y = (bf16_t*)(ws + WS_Y);
;     bf16_t* Ub = (bf16_t*)(ws + WS_U); bf16_t* Gb = (bf16_t*)(ws + WS_G); bf16_t* UZb = (bf16_t*)(ws + WS_UZ); bf16_t* Vb = (bf16_t*)(ws + WS_V);
;     bf16_t* X1 = (bf16_t*)(ws + WS_X1); bf16_t* H1 = (bf16_t*)(ws + WS_H1);
;     bf16_t* Qb = (bf16_t*)(ws + WS_Q); bf16_t* Kb = (bf16_t*)(ws + WS_K); bf16_t* Zb = (bf16_t*)(ws + WS_Z); bf16_t* VTb = (bf16_t*)(ws + WS_VT); bf16_t* OZb = (bf16_t*)(ws + WS_OZ);
;     const int lo = a.ph_lo, hi = a.ph_hi;
;     ...
;     volatile LAS unsigned* bst = (volatile LAS unsigned*)(lds + LDS_BYTES - 64);
;     if (tid < 4) bst[tid] = 0u;
.LBB0_31:
	s_ashr_i32 s5, s2, 31
	s_lshr_b32 s5, s5, 29
	s_add_i32 s5, s2, s5
	s_and_b32 s6, s5, -8
	s_ashr_i32 s4, s3, 3
	s_sub_i32 s6, s2, s6
	s_mul_i32 s4, s4, s6
	s_ashr_i32 s5, s5, 3
	s_add_i32 s84, s4, s5
	v_cmp_gt_u32_e32 vcc, 4, v0
	s_and_saveexec_b64 s[4:5], vcc
	s_cbranch_execnz .LBB0_2
	s_branch .LBB0_3
